# grid-barrier poll backoff increased: s_sleep 1 -> s_sleep 6 on top of v031
# speedup vs baseline: 1.0058x; 1.0050x over previous
; __global__ void __launch_bounds__(512, 2) fwd_megakernel(Params p) {
;     ...
;   grid.sync();
.LBB0_135:
	s_sleep 6
	global_load_dword v2, v0, s[6:7] offset:32 sc1
	s_waitcnt vmcnt(0)
	v_and_b32_e32 v2, 0xffff0000, v2
	v_cmp_ne_u32_e32 vcc, v2, v1
	s_or_b64 s[8:9], vcc, s[8:9]
	s_andn2_b64 exec, exec, s[8:9]
	s_cbranch_execnz .LBB0_135

; __device__ __forceinline__ unsigned xb_ld(unsigned* p)              { return __hip_atomic_load(p, __ATOMIC_RELAXED, __HIP_MEMORY_SCOPE_AGENT); }
; __device__ __forceinline__ void xcd_barrier_complete(unsigned* bar, unsigned x, unsigned& nloc, unsigned& nx) {
;   const unsigned G = gridDim.x * gridDim.y * gridDim.z;
;   unsigned sum, cnt, mine, sp = 0u;
;   for (;;) {
;     sum = 0u; cnt = 0u; mine = 0u;
; #pragma unroll
;     for (unsigned j = 0; j < 16; ++j) { const unsigned c = xb_ld(&bar[XB_XCNT(j)]); sum += c; cnt += (c > 0u) ? 1u : 0u; mine = (j == x) ? c : mine; }
;     if (sum == G) break;
;     __builtin_amdgcn_s_sleep(1);
;     if ((++sp & 255u) == 0u) { if (xb_ld(&bar[XB_TMO])) break; if (sp > XB_SPIN_CAP) { atomicAdd(&bar[XB_TMO], 1u); break; } }
;   }
;   nloc = mine > 0u ? mine : 1u; nx = cnt > 0u ? cnt : 1u;
; }
.LBB0_144:
	global_load_dword v15, v16, s[8:9] sc1
	global_load_dword v0, v16, s[10:11] sc1
	global_load_dword v1, v16, s[12:13] sc1
	global_load_dword v2, v16, s[14:15] sc1
	global_load_dword v3, v16, s[16:17] sc1
	global_load_dword v4, v16, s[18:19] sc1
	global_load_dword v5, v16, s[20:21] sc1
	global_load_dword v6, v16, s[22:23] sc1
	global_load_dword v7, v16, s[24:25] sc1
	global_load_dword v8, v16, s[26:27] sc1
	global_load_dword v9, v16, s[28:29] sc1
	global_load_dword v10, v16, s[30:31] sc1
	global_load_dword v11, v16, s[34:35] sc1
	global_load_dword v12, v16, s[36:37] sc1
	global_load_dword v13, v16, s[38:39] sc1
	global_load_dword v14, v16, s[40:41] sc1
	s_mov_b64 s[42:43], -1
	s_mov_b64 s[44:45], -1
	s_waitcnt vmcnt(14)
	v_add_u32_e32 v17, v0, v15
	s_waitcnt vmcnt(13)
	v_add_u32_e32 v17, v17, v1
	s_waitcnt vmcnt(12)
	v_add_u32_e32 v17, v17, v2
	s_waitcnt vmcnt(11)
	v_add_u32_e32 v17, v17, v3
	s_waitcnt vmcnt(10)
	v_add_u32_e32 v17, v17, v4
	s_waitcnt vmcnt(9)
	v_add_u32_e32 v17, v17, v5
	s_waitcnt vmcnt(8)
	v_add_u32_e32 v17, v17, v6
	s_waitcnt vmcnt(7)
	v_add_u32_e32 v17, v17, v7
	s_waitcnt vmcnt(6)
	v_add_u32_e32 v17, v17, v8
	s_waitcnt vmcnt(5)
	v_add_u32_e32 v17, v17, v9
	s_waitcnt vmcnt(4)
	v_add_u32_e32 v17, v17, v10
	s_waitcnt vmcnt(3)
	v_add_u32_e32 v17, v17, v11
	s_waitcnt vmcnt(2)
	v_add_u32_e32 v17, v17, v12
	s_waitcnt vmcnt(1)
	v_add_u32_e32 v17, v17, v13
	s_waitcnt vmcnt(0)
	v_add_u32_e32 v17, v17, v14
	v_cmp_eq_u32_e32 vcc, s0, v17
	s_cbranch_vccnz .LBB0_143
	s_and_b32 s2, s1, 0xff
	s_cmp_eq_u32 s2, 0
	s_mov_b64 s[46:47], -1
	s_sleep 6
	s_cbranch_scc0 .LBB0_148
	global_load_dword v17, v16, s[6:7] sc1
	s_waitcnt vmcnt(0)
	v_cmp_eq_u32_e32 vcc, 0, v17
	s_cbranch_vccnz .LBB0_150
	s_mov_b64 s[46:47], 0

; __device__ __forceinline__ unsigned xb_ld(unsigned* p)              { return __hip_atomic_load(p, __ATOMIC_RELAXED, __HIP_MEMORY_SCOPE_AGENT); }
; __device__ __forceinline__ unsigned xb_add(unsigned* p, unsigned v) { return __hip_atomic_fetch_add(p, v, __ATOMIC_RELAXED, __HIP_MEMORY_SCOPE_AGENT); }
; #define XB_SPIN(cond, bar) do { unsigned _sp = 0; while (cond) { __builtin_amdgcn_s_sleep(1); \
;     if ((++_sp & 255u) == 0u) { if (xb_ld(&(bar)[XB_TMO])) break; if (_sp > XB_SPIN_CAP) { atomicAdd(&(bar)[XB_TMO], 1u); break; } } } } while (0)
; __device__ __forceinline__ void xcd_barrier(const XcdBarrier& b) {
;     ...
;     const unsigned old = xb_add(&bar[XB_XSUB(b.x)], 1u);
;     const unsigned gen = old / nloc;
;     if (old + 1u == (gen + 1u) * nloc) {
;       __builtin_amdgcn_fence(__ATOMIC_RELEASE, "agent");
;       asm volatile("s_waitcnt vmcnt(0)" ::: "memory");
;       const unsigned og = xb_add(&bar[XB_TOP], 1u);
;       const unsigned tg = og / nx;
;       if (og + 1u == (tg + 1u) * nx) xb_add(&bar[XB_TOPGEN], 1u);
;       else XB_SPIN(xb_ld(&bar[XB_TOPGEN]) == tg, bar);
;       __builtin_amdgcn_fence(__ATOMIC_ACQUIRE, "agent");
;       xb_add(&bar[XB_XGEN(b.x)], 1u);
;       asm volatile("s_waitcnt vmcnt(0)" ::: "memory");
;     } else {
;       XB_SPIN(xb_ld(&bar[XB_XGEN(b.x)]) == gen, bar);
;       __builtin_amdgcn_fence(__ATOMIC_ACQUIRE, "agent");
;       asm volatile("s_waitcnt vmcnt(0)" ::: "memory");
;     }
.LBB0_162:
	s_and_b32 s1, s0, 0xff
	s_mov_b64 s[20:21], -1
	s_cmp_lg_u32 s1, 0
	s_mov_b64 s[24:25], -1
	s_sleep 6
	s_cbranch_scc1 .LBB0_165
	global_load_dword v2, v0, s[12:13] sc1
	s_waitcnt vmcnt(0)
	v_cmp_eq_u32_e32 vcc, 0, v2
	s_cbranch_vccnz .LBB0_167
	s_mov_b64 s[24:25], 0
	s_mov_b64 s[22:23], -1

; __device__ __forceinline__ unsigned xb_ld(unsigned* p)              { return __hip_atomic_load(p, __ATOMIC_RELAXED, __HIP_MEMORY_SCOPE_AGENT); }
; __device__ __forceinline__ unsigned xb_add(unsigned* p, unsigned v) { return __hip_atomic_fetch_add(p, v, __ATOMIC_RELAXED, __HIP_MEMORY_SCOPE_AGENT); }
; #define XB_SPIN(cond, bar) do { unsigned _sp = 0; while (cond) { __builtin_amdgcn_s_sleep(1); \
;     if ((++_sp & 255u) == 0u) { if (xb_ld(&(bar)[XB_TMO])) break; if (_sp > XB_SPIN_CAP) { atomicAdd(&(bar)[XB_TMO], 1u); break; } } } } while (0)
; __device__ __forceinline__ void xcd_barrier(const XcdBarrier& b) {
;     ...
;     const unsigned old = xb_add(&bar[XB_XSUB(b.x)], 1u);
;     const unsigned gen = old / nloc;
;     if (old + 1u == (gen + 1u) * nloc) {
;       __builtin_amdgcn_fence(__ATOMIC_RELEASE, "agent");
;       asm volatile("s_waitcnt vmcnt(0)" ::: "memory");
;       const unsigned og = xb_add(&bar[XB_TOP], 1u);
;       const unsigned tg = og / nx;
;       if (og + 1u == (tg + 1u) * nx) xb_add(&bar[XB_TOPGEN], 1u);
;       else XB_SPIN(xb_ld(&bar[XB_TOPGEN]) == tg, bar);
;       __builtin_amdgcn_fence(__ATOMIC_ACQUIRE, "agent");
;       xb_add(&bar[XB_XGEN(b.x)], 1u);
;       asm volatile("s_waitcnt vmcnt(0)" ::: "memory");
;     } else {
;       XB_SPIN(xb_ld(&bar[XB_XGEN(b.x)]) == gen, bar);
;       __builtin_amdgcn_fence(__ATOMIC_ACQUIRE, "agent");
;       asm volatile("s_waitcnt vmcnt(0)" ::: "memory");
;     }
.LBB0_179:
	s_and_b32 s1, s0, 0xff
	s_cmp_lg_u32 s1, 0
	s_mov_b64 s[22:23], -1
	s_sleep 6
	s_cbranch_scc1 .LBB0_182
	global_load_dword v1, v0, s[12:13] sc1
	s_waitcnt vmcnt(0)
	v_cmp_eq_u32_e32 vcc, 0, v1
	s_cbranch_vccnz .LBB0_184
	s_mov_b64 s[22:23], 0
	s_mov_b64 s[20:21], -1

; __device__ __forceinline__ unsigned xb_ld(unsigned* p)              { return __hip_atomic_load(p, __ATOMIC_RELAXED, __HIP_MEMORY_SCOPE_AGENT); }
; __device__ __forceinline__ void xcd_barrier_complete(unsigned* bar, unsigned x, unsigned& nloc, unsigned& nx) {
;   const unsigned G = gridDim.x * gridDim.y * gridDim.z;
;   unsigned sum, cnt, mine, sp = 0u;
;   for (;;) {
;     sum = 0u; cnt = 0u; mine = 0u;
; #pragma unroll
;     for (unsigned j = 0; j < 16; ++j) { const unsigned c = xb_ld(&bar[XB_XCNT(j)]); sum += c; cnt += (c > 0u) ? 1u : 0u; mine = (j == x) ? c : mine; }
;     if (sum == G) break;
;     __builtin_amdgcn_s_sleep(1);
;     if ((++sp & 255u) == 0u) { if (xb_ld(&bar[XB_TMO])) break; if (sp > XB_SPIN_CAP) { atomicAdd(&bar[XB_TMO], 1u); break; } }
;   }
;   nloc = mine > 0u ? mine : 1u; nx = cnt > 0u ? cnt : 1u;
; }
.LBB0_552:
	global_load_dword v15, v16, s[8:9] sc1
	s_waitcnt lgkmcnt(0)
	global_load_dword v0, v16, s[10:11] sc1
	global_load_dword v1, v16, s[12:13] sc1
	global_load_dword v2, v16, s[14:15] sc1
	global_load_dword v3, v16, s[16:17] sc1
	global_load_dword v4, v16, s[18:19] sc1
	global_load_dword v5, v16, s[20:21] sc1
	global_load_dword v6, v16, s[22:23] sc1
	global_load_dword v7, v16, s[24:25] sc1
	global_load_dword v8, v16, s[26:27] sc1
	global_load_dword v9, v16, s[28:29] sc1
	global_load_dword v10, v16, s[30:31] sc1
	global_load_dword v11, v16, s[34:35] sc1
	global_load_dword v12, v16, s[36:37] sc1
	global_load_dword v13, v16, s[38:39] sc1
	global_load_dword v14, v16, s[40:41] sc1
	s_mov_b64 s[42:43], -1
	s_mov_b64 s[44:45], -1
	s_waitcnt vmcnt(14)
	v_add_u32_e32 v17, v0, v15
	s_waitcnt vmcnt(13)
	v_add_u32_e32 v17, v17, v1
	s_waitcnt vmcnt(12)
	v_add_u32_e32 v17, v17, v2
	s_waitcnt vmcnt(11)
	v_add_u32_e32 v17, v17, v3
	s_waitcnt vmcnt(10)
	v_add_u32_e32 v17, v17, v4
	s_waitcnt vmcnt(9)
	v_add_u32_e32 v17, v17, v5
	s_waitcnt vmcnt(8)
	v_add_u32_e32 v17, v17, v6
	s_waitcnt vmcnt(7)
	v_add_u32_e32 v17, v17, v7
	s_waitcnt vmcnt(6)
	v_add_u32_e32 v17, v17, v8
	s_waitcnt vmcnt(5)
	v_add_u32_e32 v17, v17, v9
	s_waitcnt vmcnt(4)
	v_add_u32_e32 v17, v17, v10
	s_waitcnt vmcnt(3)
	v_add_u32_e32 v17, v17, v11
	s_waitcnt vmcnt(2)
	v_add_u32_e32 v17, v17, v12
	s_waitcnt vmcnt(1)
	v_add_u32_e32 v17, v17, v13
	s_waitcnt vmcnt(0)
	v_add_u32_e32 v17, v17, v14
	v_cmp_eq_u32_e32 vcc, s0, v17
	s_cbranch_vccnz .LBB0_551
	s_and_b32 s2, s1, 0xff
	s_cmp_eq_u32 s2, 0
	s_mov_b64 s[46:47], -1
	s_sleep 6
	s_cbranch_scc0 .LBB0_556
	global_load_dword v17, v16, s[6:7] sc1
	s_waitcnt vmcnt(0)
	v_cmp_eq_u32_e32 vcc, 0, v17
	s_cbranch_vccnz .LBB0_558
	s_mov_b64 s[46:47], 0

; __device__ __forceinline__ unsigned xb_ld(unsigned* p)              { return __hip_atomic_load(p, __ATOMIC_RELAXED, __HIP_MEMORY_SCOPE_AGENT); }
; __device__ __forceinline__ void xcd_barrier_complete(unsigned* bar, unsigned x, unsigned& nloc, unsigned& nx) {
;   const unsigned G = gridDim.x * gridDim.y * gridDim.z;
;   unsigned sum, cnt, mine, sp = 0u;
;   for (;;) {
;     sum = 0u; cnt = 0u; mine = 0u;
; #pragma unroll
;     for (unsigned j = 0; j < 16; ++j) { const unsigned c = xb_ld(&bar[XB_XCNT(j)]); sum += c; cnt += (c > 0u) ? 1u : 0u; mine = (j == x) ? c : mine; }
;     if (sum == G) break;
;     __builtin_amdgcn_s_sleep(1);
;     if ((++sp & 255u) == 0u) { if (xb_ld(&bar[XB_TMO])) break; if (sp > XB_SPIN_CAP) { atomicAdd(&bar[XB_TMO], 1u); break; } }
;   }
;   nloc = mine > 0u ? mine : 1u; nx = cnt > 0u ? cnt : 1u;
; }
.LBB0_679:
	global_load_dword v15, v16, s[8:9] sc1
	s_waitcnt lgkmcnt(0)
	global_load_dword v0, v16, s[10:11] sc1
	global_load_dword v1, v16, s[12:13] sc1
	global_load_dword v2, v16, s[16:17] sc1
	global_load_dword v3, v16, s[18:19] sc1
	global_load_dword v4, v16, s[20:21] sc1
	global_load_dword v5, v16, s[22:23] sc1
	global_load_dword v6, v16, s[24:25] sc1
	global_load_dword v7, v16, s[26:27] sc1
	global_load_dword v8, v16, s[28:29] sc1
	global_load_dword v9, v16, s[30:31] sc1
	global_load_dword v10, v16, s[34:35] sc1
	global_load_dword v11, v16, s[36:37] sc1
	global_load_dword v12, v16, s[38:39] sc1
	global_load_dword v13, v16, s[40:41] sc1
	global_load_dword v14, v16, s[42:43] sc1
	s_mov_b64 s[44:45], -1
	s_mov_b64 s[46:47], -1
	s_waitcnt vmcnt(14)
	v_add_u32_e32 v17, v0, v15
	s_waitcnt vmcnt(13)
	v_add_u32_e32 v17, v17, v1
	s_waitcnt vmcnt(12)
	v_add_u32_e32 v17, v17, v2
	s_waitcnt vmcnt(11)
	v_add_u32_e32 v17, v17, v3
	s_waitcnt vmcnt(10)
	v_add_u32_e32 v17, v17, v4
	s_waitcnt vmcnt(9)
	v_add_u32_e32 v17, v17, v5
	s_waitcnt vmcnt(8)
	v_add_u32_e32 v17, v17, v6
	s_waitcnt vmcnt(7)
	v_add_u32_e32 v17, v17, v7
	s_waitcnt vmcnt(6)
	v_add_u32_e32 v17, v17, v8
	s_waitcnt vmcnt(5)
	v_add_u32_e32 v17, v17, v9
	s_waitcnt vmcnt(4)
	v_add_u32_e32 v17, v17, v10
	s_waitcnt vmcnt(3)
	v_add_u32_e32 v17, v17, v11
	s_waitcnt vmcnt(2)
	v_add_u32_e32 v17, v17, v12
	s_waitcnt vmcnt(1)
	v_add_u32_e32 v17, v17, v13
	s_waitcnt vmcnt(0)
	v_add_u32_e32 v17, v17, v14
	v_cmp_eq_u32_e32 vcc, s0, v17
	s_cbranch_vccnz .LBB0_678
	s_and_b32 s2, s1, 0xff
	s_cmp_eq_u32 s2, 0
	s_mov_b64 s[48:49], -1
	s_sleep 6
	s_cbranch_scc0 .LBB0_683
	global_load_dword v17, v16, s[6:7] sc1
	s_waitcnt vmcnt(0)
	v_cmp_eq_u32_e32 vcc, 0, v17
	s_cbranch_vccnz .LBB0_685
	s_mov_b64 s[48:49], 0

; __device__ __forceinline__ unsigned xb_ld(unsigned* p)              { return __hip_atomic_load(p, __ATOMIC_RELAXED, __HIP_MEMORY_SCOPE_AGENT); }
; __device__ __forceinline__ unsigned xb_add(unsigned* p, unsigned v) { return __hip_atomic_fetch_add(p, v, __ATOMIC_RELAXED, __HIP_MEMORY_SCOPE_AGENT); }
; #define XB_SPIN(cond, bar) do { unsigned _sp = 0; while (cond) { __builtin_amdgcn_s_sleep(1); \
;     if ((++_sp & 255u) == 0u) { if (xb_ld(&(bar)[XB_TMO])) break; if (_sp > XB_SPIN_CAP) { atomicAdd(&(bar)[XB_TMO], 1u); break; } } } } while (0)
; __device__ __forceinline__ void xcd_barrier(const XcdBarrier& b) {
;     ...
;     const unsigned old = xb_add(&bar[XB_XSUB(b.x)], 1u);
;     const unsigned gen = old / nloc;
;     if (old + 1u == (gen + 1u) * nloc) {
;       __builtin_amdgcn_fence(__ATOMIC_RELEASE, "agent");
;       asm volatile("s_waitcnt vmcnt(0)" ::: "memory");
;       const unsigned og = xb_add(&bar[XB_TOP], 1u);
;       const unsigned tg = og / nx;
;       if (og + 1u == (tg + 1u) * nx) xb_add(&bar[XB_TOPGEN], 1u);
;       else XB_SPIN(xb_ld(&bar[XB_TOPGEN]) == tg, bar);
;       __builtin_amdgcn_fence(__ATOMIC_ACQUIRE, "agent");
;       xb_add(&bar[XB_XGEN(b.x)], 1u);
;       asm volatile("s_waitcnt vmcnt(0)" ::: "memory");
;     } else {
;       XB_SPIN(xb_ld(&bar[XB_XGEN(b.x)]) == gen, bar);
;       __builtin_amdgcn_fence(__ATOMIC_ACQUIRE, "agent");
;       asm volatile("s_waitcnt vmcnt(0)" ::: "memory");
;     }
.LBB0_697:
	s_and_b32 s1, s0, 0xff
	s_mov_b64 s[22:23], -1
	s_cmp_lg_u32 s1, 0
	s_mov_b64 s[26:27], -1
	s_sleep 6
	s_cbranch_scc1 .LBB0_700
	global_load_dword v2, v0, s[12:13] sc1
	s_waitcnt vmcnt(0)
	v_cmp_eq_u32_e32 vcc, 0, v2
	s_cbranch_vccnz .LBB0_702
	s_mov_b64 s[26:27], 0
	s_mov_b64 s[24:25], -1

; __device__ __forceinline__ unsigned xb_ld(unsigned* p)              { return __hip_atomic_load(p, __ATOMIC_RELAXED, __HIP_MEMORY_SCOPE_AGENT); }
; __device__ __forceinline__ unsigned xb_add(unsigned* p, unsigned v) { return __hip_atomic_fetch_add(p, v, __ATOMIC_RELAXED, __HIP_MEMORY_SCOPE_AGENT); }
; #define XB_SPIN(cond, bar) do { unsigned _sp = 0; while (cond) { __builtin_amdgcn_s_sleep(1); \
;     if ((++_sp & 255u) == 0u) { if (xb_ld(&(bar)[XB_TMO])) break; if (_sp > XB_SPIN_CAP) { atomicAdd(&(bar)[XB_TMO], 1u); break; } } } } while (0)
; __device__ __forceinline__ void xcd_barrier(const XcdBarrier& b) {
;     ...
;     const unsigned old = xb_add(&bar[XB_XSUB(b.x)], 1u);
;     const unsigned gen = old / nloc;
;     if (old + 1u == (gen + 1u) * nloc) {
;       __builtin_amdgcn_fence(__ATOMIC_RELEASE, "agent");
;       asm volatile("s_waitcnt vmcnt(0)" ::: "memory");
;       const unsigned og = xb_add(&bar[XB_TOP], 1u);
;       const unsigned tg = og / nx;
;       if (og + 1u == (tg + 1u) * nx) xb_add(&bar[XB_TOPGEN], 1u);
;       else XB_SPIN(xb_ld(&bar[XB_TOPGEN]) == tg, bar);
;       __builtin_amdgcn_fence(__ATOMIC_ACQUIRE, "agent");
;       xb_add(&bar[XB_XGEN(b.x)], 1u);
;       asm volatile("s_waitcnt vmcnt(0)" ::: "memory");
;     } else {
;       XB_SPIN(xb_ld(&bar[XB_XGEN(b.x)]) == gen, bar);
;       __builtin_amdgcn_fence(__ATOMIC_ACQUIRE, "agent");
;       asm volatile("s_waitcnt vmcnt(0)" ::: "memory");
;     }
.LBB0_714:
	s_and_b32 s1, s0, 0xff
	s_cmp_lg_u32 s1, 0
	s_mov_b64 s[24:25], -1
	s_sleep 6
	s_cbranch_scc1 .LBB0_717
	global_load_dword v1, v0, s[12:13] sc1
	s_waitcnt vmcnt(0)
	v_cmp_eq_u32_e32 vcc, 0, v1
	s_cbranch_vccnz .LBB0_719
	s_mov_b64 s[24:25], 0
	s_mov_b64 s[22:23], -1

; __device__ __forceinline__ unsigned xb_ld(unsigned* p)              { return __hip_atomic_load(p, __ATOMIC_RELAXED, __HIP_MEMORY_SCOPE_AGENT); }
; __device__ __forceinline__ void xcd_barrier_complete(unsigned* bar, unsigned x, unsigned& nloc, unsigned& nx) {
;   const unsigned G = gridDim.x * gridDim.y * gridDim.z;
;   unsigned sum, cnt, mine, sp = 0u;
;   for (;;) {
;     sum = 0u; cnt = 0u; mine = 0u;
; #pragma unroll
;     for (unsigned j = 0; j < 16; ++j) { const unsigned c = xb_ld(&bar[XB_XCNT(j)]); sum += c; cnt += (c > 0u) ? 1u : 0u; mine = (j == x) ? c : mine; }
;     if (sum == G) break;
;     __builtin_amdgcn_s_sleep(1);
;     if ((++sp & 255u) == 0u) { if (xb_ld(&bar[XB_TMO])) break; if (sp > XB_SPIN_CAP) { atomicAdd(&bar[XB_TMO], 1u); break; } }
;   }
;   nloc = mine > 0u ? mine : 1u; nx = cnt > 0u ? cnt : 1u;
; }
.LBB0_775:
	global_load_dword v15, v16, s[16:17] sc1
	s_waitcnt lgkmcnt(0)
	global_load_dword v0, v16, s[18:19] sc1
	global_load_dword v1, v16, s[20:21] sc1
	global_load_dword v2, v16, s[22:23] sc1
	global_load_dword v3, v16, s[24:25] sc1
	global_load_dword v4, v16, s[26:27] sc1
	global_load_dword v5, v16, s[30:31] sc1
	global_load_dword v6, v16, s[34:35] sc1
	global_load_dword v7, v16, s[36:37] sc1
	global_load_dword v8, v16, s[38:39] sc1
	global_load_dword v9, v16, s[40:41] sc1
	global_load_dword v10, v16, s[42:43] sc1
	global_load_dword v11, v16, s[44:45] sc1
	global_load_dword v12, v16, s[46:47] sc1
	global_load_dword v13, v16, s[48:49] sc1
	global_load_dword v14, v16, s[50:51] sc1
	s_mov_b64 s[52:53], -1
	s_mov_b64 s[54:55], -1
	s_waitcnt vmcnt(14)
	v_add_u32_e32 v17, v0, v15
	s_waitcnt vmcnt(13)
	v_add_u32_e32 v17, v17, v1
	s_waitcnt vmcnt(12)
	v_add_u32_e32 v17, v17, v2
	s_waitcnt vmcnt(11)
	v_add_u32_e32 v17, v17, v3
	s_waitcnt vmcnt(10)
	v_add_u32_e32 v17, v17, v4
	s_waitcnt vmcnt(9)
	v_add_u32_e32 v17, v17, v5
	s_waitcnt vmcnt(8)
	v_add_u32_e32 v17, v17, v6
	s_waitcnt vmcnt(7)
	v_add_u32_e32 v17, v17, v7
	s_waitcnt vmcnt(6)
	v_add_u32_e32 v17, v17, v8
	s_waitcnt vmcnt(5)
	v_add_u32_e32 v17, v17, v9
	s_waitcnt vmcnt(4)
	v_add_u32_e32 v17, v17, v10
	s_waitcnt vmcnt(3)
	v_add_u32_e32 v17, v17, v11
	s_waitcnt vmcnt(2)
	v_add_u32_e32 v17, v17, v12
	s_waitcnt vmcnt(1)
	v_add_u32_e32 v17, v17, v13
	s_waitcnt vmcnt(0)
	v_add_u32_e32 v17, v17, v14
	v_cmp_eq_u32_e32 vcc, s0, v17
	s_cbranch_vccnz .LBB0_774
	s_and_b32 s2, s1, 0xff
	s_cmp_eq_u32 s2, 0
	s_mov_b64 s[56:57], -1
	s_sleep 6
	s_cbranch_scc0 .LBB0_779
	global_load_dword v17, v16, s[6:7] sc1
	s_waitcnt vmcnt(0)
	v_cmp_eq_u32_e32 vcc, 0, v17
	s_cbranch_vccnz .LBB0_781
	s_mov_b64 s[56:57], 0

; __device__ __forceinline__ unsigned xb_ld(unsigned* p)              { return __hip_atomic_load(p, __ATOMIC_RELAXED, __HIP_MEMORY_SCOPE_AGENT); }
; __device__ __forceinline__ unsigned xb_add(unsigned* p, unsigned v) { return __hip_atomic_fetch_add(p, v, __ATOMIC_RELAXED, __HIP_MEMORY_SCOPE_AGENT); }
; #define XB_SPIN(cond, bar) do { unsigned _sp = 0; while (cond) { __builtin_amdgcn_s_sleep(1); \
;     if ((++_sp & 255u) == 0u) { if (xb_ld(&(bar)[XB_TMO])) break; if (_sp > XB_SPIN_CAP) { atomicAdd(&(bar)[XB_TMO], 1u); break; } } } } while (0)
; __device__ __forceinline__ void xcd_barrier(const XcdBarrier& b) {
;     ...
;     const unsigned old = xb_add(&bar[XB_XSUB(b.x)], 1u);
;     const unsigned gen = old / nloc;
;     if (old + 1u == (gen + 1u) * nloc) {
;       __builtin_amdgcn_fence(__ATOMIC_RELEASE, "agent");
;       asm volatile("s_waitcnt vmcnt(0)" ::: "memory");
;       const unsigned og = xb_add(&bar[XB_TOP], 1u);
;       const unsigned tg = og / nx;
;       if (og + 1u == (tg + 1u) * nx) xb_add(&bar[XB_TOPGEN], 1u);
;       else XB_SPIN(xb_ld(&bar[XB_TOPGEN]) == tg, bar);
;       __builtin_amdgcn_fence(__ATOMIC_ACQUIRE, "agent");
;       xb_add(&bar[XB_XGEN(b.x)], 1u);
;       asm volatile("s_waitcnt vmcnt(0)" ::: "memory");
;     } else {
;       XB_SPIN(xb_ld(&bar[XB_XGEN(b.x)]) == gen, bar);
;       __builtin_amdgcn_fence(__ATOMIC_ACQUIRE, "agent");
;       asm volatile("s_waitcnt vmcnt(0)" ::: "memory");
;     }
.LBB0_793:
	s_and_b32 s1, s0, 0xff
	s_mov_b64 s[30:31], -1
	s_cmp_lg_u32 s1, 0
	s_mov_b64 s[36:37], -1
	s_sleep 6
	s_cbranch_scc1 .LBB0_796
	global_load_dword v2, v0, s[20:21] sc1
	s_waitcnt vmcnt(0)
	v_cmp_eq_u32_e32 vcc, 0, v2
	s_cbranch_vccnz .LBB0_798
	s_mov_b64 s[36:37], 0
	s_mov_b64 s[34:35], -1

; __device__ __forceinline__ unsigned xb_ld(unsigned* p)              { return __hip_atomic_load(p, __ATOMIC_RELAXED, __HIP_MEMORY_SCOPE_AGENT); }
; __device__ __forceinline__ unsigned xb_add(unsigned* p, unsigned v) { return __hip_atomic_fetch_add(p, v, __ATOMIC_RELAXED, __HIP_MEMORY_SCOPE_AGENT); }
; #define XB_SPIN(cond, bar) do { unsigned _sp = 0; while (cond) { __builtin_amdgcn_s_sleep(1); \
;     if ((++_sp & 255u) == 0u) { if (xb_ld(&(bar)[XB_TMO])) break; if (_sp > XB_SPIN_CAP) { atomicAdd(&(bar)[XB_TMO], 1u); break; } } } } while (0)
; __device__ __forceinline__ void xcd_barrier(const XcdBarrier& b) {
;     ...
;     const unsigned old = xb_add(&bar[XB_XSUB(b.x)], 1u);
;     const unsigned gen = old / nloc;
;     if (old + 1u == (gen + 1u) * nloc) {
;       __builtin_amdgcn_fence(__ATOMIC_RELEASE, "agent");
;       asm volatile("s_waitcnt vmcnt(0)" ::: "memory");
;       const unsigned og = xb_add(&bar[XB_TOP], 1u);
;       const unsigned tg = og / nx;
;       if (og + 1u == (tg + 1u) * nx) xb_add(&bar[XB_TOPGEN], 1u);
;       else XB_SPIN(xb_ld(&bar[XB_TOPGEN]) == tg, bar);
;       __builtin_amdgcn_fence(__ATOMIC_ACQUIRE, "agent");
;       xb_add(&bar[XB_XGEN(b.x)], 1u);
;       asm volatile("s_waitcnt vmcnt(0)" ::: "memory");
;     } else {
;       XB_SPIN(xb_ld(&bar[XB_XGEN(b.x)]) == gen, bar);
;       __builtin_amdgcn_fence(__ATOMIC_ACQUIRE, "agent");
;       asm volatile("s_waitcnt vmcnt(0)" ::: "memory");
;     }
.LBB0_810:
	s_and_b32 s1, s0, 0xff
	s_cmp_lg_u32 s1, 0
	s_mov_b64 s[34:35], -1
	s_sleep 6
	s_cbranch_scc1 .LBB0_813
	global_load_dword v1, v0, s[20:21] sc1
	s_waitcnt vmcnt(0)
	v_cmp_eq_u32_e32 vcc, 0, v1
	s_cbranch_vccnz .LBB0_815
	s_mov_b64 s[34:35], 0
	s_mov_b64 s[30:31], -1

; __device__ __forceinline__ unsigned xb_ld(unsigned* p)              { return __hip_atomic_load(p, __ATOMIC_RELAXED, __HIP_MEMORY_SCOPE_AGENT); }
; __device__ __forceinline__ void xcd_barrier_complete(unsigned* bar, unsigned x, unsigned& nloc, unsigned& nx) {
;   const unsigned G = gridDim.x * gridDim.y * gridDim.z;
;   unsigned sum, cnt, mine, sp = 0u;
;   for (;;) {
;     sum = 0u; cnt = 0u; mine = 0u;
; #pragma unroll
;     for (unsigned j = 0; j < 16; ++j) { const unsigned c = xb_ld(&bar[XB_XCNT(j)]); sum += c; cnt += (c > 0u) ? 1u : 0u; mine = (j == x) ? c : mine; }
;     if (sum == G) break;
;     __builtin_amdgcn_s_sleep(1);
;     if ((++sp & 255u) == 0u) { if (xb_ld(&bar[XB_TMO])) break; if (sp > XB_SPIN_CAP) { atomicAdd(&bar[XB_TMO], 1u); break; } }
;   }
;   nloc = mine > 0u ? mine : 1u; nx = cnt > 0u ? cnt : 1u;
; }
.LBB0_1012:
	global_load_dword v15, v16, s[12:13] sc1
	s_waitcnt lgkmcnt(0)
	global_load_dword v0, v16, s[16:17] sc1
	global_load_dword v1, v16, s[18:19] sc1
	global_load_dword v2, v16, s[20:21] sc1
	global_load_dword v3, v16, s[22:23] sc1
	global_load_dword v4, v16, s[24:25] sc1
	global_load_dword v5, v16, s[26:27] sc1
	global_load_dword v6, v16, s[30:31] sc1
	global_load_dword v7, v16, s[34:35] sc1
	global_load_dword v8, v16, s[36:37] sc1
	global_load_dword v9, v16, s[38:39] sc1
	global_load_dword v10, v16, s[40:41] sc1
	global_load_dword v11, v16, s[42:43] sc1
	global_load_dword v12, v16, s[44:45] sc1
	global_load_dword v13, v16, s[46:47] sc1
	global_load_dword v14, v16, s[48:49] sc1
	s_mov_b64 s[50:51], -1
	s_mov_b64 s[52:53], -1
	s_waitcnt vmcnt(14)
	v_add_u32_e32 v17, v0, v15
	s_waitcnt vmcnt(13)
	v_add_u32_e32 v17, v17, v1
	s_waitcnt vmcnt(12)
	v_add_u32_e32 v17, v17, v2
	s_waitcnt vmcnt(11)
	v_add_u32_e32 v17, v17, v3
	s_waitcnt vmcnt(10)
	v_add_u32_e32 v17, v17, v4
	s_waitcnt vmcnt(9)
	v_add_u32_e32 v17, v17, v5
	s_waitcnt vmcnt(8)
	v_add_u32_e32 v17, v17, v6
	s_waitcnt vmcnt(7)
	v_add_u32_e32 v17, v17, v7
	s_waitcnt vmcnt(6)
	v_add_u32_e32 v17, v17, v8
	s_waitcnt vmcnt(5)
	v_add_u32_e32 v17, v17, v9
	s_waitcnt vmcnt(4)
	v_add_u32_e32 v17, v17, v10
	s_waitcnt vmcnt(3)
	v_add_u32_e32 v17, v17, v11
	s_waitcnt vmcnt(2)
	v_add_u32_e32 v17, v17, v12
	s_waitcnt vmcnt(1)
	v_add_u32_e32 v17, v17, v13
	s_waitcnt vmcnt(0)
	v_add_u32_e32 v17, v17, v14
	v_cmp_eq_u32_e32 vcc, s0, v17
	s_cbranch_vccnz .LBB0_1011
	s_and_b32 s2, s1, 0xff
	s_cmp_eq_u32 s2, 0
	s_mov_b64 s[54:55], -1
	s_sleep 6
	s_cbranch_scc0 .LBB0_1016
	global_load_dword v17, v16, s[8:9] sc1
	s_waitcnt vmcnt(0)
	v_cmp_eq_u32_e32 vcc, 0, v17
	s_cbranch_vccnz .LBB0_1018
	s_mov_b64 s[54:55], 0

; __device__ __forceinline__ unsigned xb_ld(unsigned* p)              { return __hip_atomic_load(p, __ATOMIC_RELAXED, __HIP_MEMORY_SCOPE_AGENT); }
; __device__ __forceinline__ unsigned xb_add(unsigned* p, unsigned v) { return __hip_atomic_fetch_add(p, v, __ATOMIC_RELAXED, __HIP_MEMORY_SCOPE_AGENT); }
; #define XB_SPIN(cond, bar) do { unsigned _sp = 0; while (cond) { __builtin_amdgcn_s_sleep(1); \
;     if ((++_sp & 255u) == 0u) { if (xb_ld(&(bar)[XB_TMO])) break; if (_sp > XB_SPIN_CAP) { atomicAdd(&(bar)[XB_TMO], 1u); break; } } } } while (0)
; __device__ __forceinline__ void xcd_barrier(const XcdBarrier& b) {
;     ...
;     const unsigned old = xb_add(&bar[XB_XSUB(b.x)], 1u);
;     const unsigned gen = old / nloc;
;     if (old + 1u == (gen + 1u) * nloc) {
;       __builtin_amdgcn_fence(__ATOMIC_RELEASE, "agent");
;       asm volatile("s_waitcnt vmcnt(0)" ::: "memory");
;       const unsigned og = xb_add(&bar[XB_TOP], 1u);
;       const unsigned tg = og / nx;
;       if (og + 1u == (tg + 1u) * nx) xb_add(&bar[XB_TOPGEN], 1u);
;       else XB_SPIN(xb_ld(&bar[XB_TOPGEN]) == tg, bar);
;       __builtin_amdgcn_fence(__ATOMIC_ACQUIRE, "agent");
;       xb_add(&bar[XB_XGEN(b.x)], 1u);
;       asm volatile("s_waitcnt vmcnt(0)" ::: "memory");
;     } else {
;       XB_SPIN(xb_ld(&bar[XB_XGEN(b.x)]) == gen, bar);
;       __builtin_amdgcn_fence(__ATOMIC_ACQUIRE, "agent");
;       asm volatile("s_waitcnt vmcnt(0)" ::: "memory");
;     }
.LBB0_1030:
	s_and_b32 s1, s0, 0xff
	s_mov_b64 s[26:27], -1
	s_cmp_lg_u32 s1, 0
	s_mov_b64 s[34:35], -1
	s_sleep 6
	s_cbranch_scc1 .LBB0_1033
	global_load_dword v2, v0, s[18:19] sc1
	s_waitcnt vmcnt(0)
	v_cmp_eq_u32_e32 vcc, 0, v2
	s_cbranch_vccnz .LBB0_1035
	s_mov_b64 s[34:35], 0
	s_mov_b64 s[30:31], -1

; __device__ __forceinline__ unsigned xb_ld(unsigned* p)              { return __hip_atomic_load(p, __ATOMIC_RELAXED, __HIP_MEMORY_SCOPE_AGENT); }
; __device__ __forceinline__ unsigned xb_add(unsigned* p, unsigned v) { return __hip_atomic_fetch_add(p, v, __ATOMIC_RELAXED, __HIP_MEMORY_SCOPE_AGENT); }
; #define XB_SPIN(cond, bar) do { unsigned _sp = 0; while (cond) { __builtin_amdgcn_s_sleep(1); \
;     if ((++_sp & 255u) == 0u) { if (xb_ld(&(bar)[XB_TMO])) break; if (_sp > XB_SPIN_CAP) { atomicAdd(&(bar)[XB_TMO], 1u); break; } } } } while (0)
; __device__ __forceinline__ void xcd_barrier(const XcdBarrier& b) {
;     ...
;     const unsigned old = xb_add(&bar[XB_XSUB(b.x)], 1u);
;     const unsigned gen = old / nloc;
;     if (old + 1u == (gen + 1u) * nloc) {
;       __builtin_amdgcn_fence(__ATOMIC_RELEASE, "agent");
;       asm volatile("s_waitcnt vmcnt(0)" ::: "memory");
;       const unsigned og = xb_add(&bar[XB_TOP], 1u);
;       const unsigned tg = og / nx;
;       if (og + 1u == (tg + 1u) * nx) xb_add(&bar[XB_TOPGEN], 1u);
;       else XB_SPIN(xb_ld(&bar[XB_TOPGEN]) == tg, bar);
;       __builtin_amdgcn_fence(__ATOMIC_ACQUIRE, "agent");
;       xb_add(&bar[XB_XGEN(b.x)], 1u);
;       asm volatile("s_waitcnt vmcnt(0)" ::: "memory");
;     } else {
;       XB_SPIN(xb_ld(&bar[XB_XGEN(b.x)]) == gen, bar);
;       __builtin_amdgcn_fence(__ATOMIC_ACQUIRE, "agent");
;       asm volatile("s_waitcnt vmcnt(0)" ::: "memory");
;     }
.LBB0_1047:
	s_and_b32 s1, s0, 0xff
	s_cmp_lg_u32 s1, 0
	s_mov_b64 s[30:31], -1
	s_sleep 6
	s_cbranch_scc1 .LBB0_1050
	global_load_dword v1, v0, s[18:19] sc1
	s_waitcnt vmcnt(0)
	v_cmp_eq_u32_e32 vcc, 0, v1
	s_cbranch_vccnz .LBB0_1052
	s_mov_b64 s[30:31], 0
	s_mov_b64 s[26:27], -1

; __device__ __forceinline__ unsigned xb_ld(unsigned* p)              { return __hip_atomic_load(p, __ATOMIC_RELAXED, __HIP_MEMORY_SCOPE_AGENT); }
; __device__ __forceinline__ void xcd_barrier_complete(unsigned* bar, unsigned x, unsigned& nloc, unsigned& nx) {
;     ...
;   for (;;) {
;     sum = 0u; cnt = 0u; mine = 0u;
; #pragma unroll
;     for (unsigned j = 0; j < 16; ++j) { const unsigned c = xb_ld(&bar[XB_XCNT(j)]); sum += c; cnt += (c > 0u) ? 1u : 0u; mine = (j == x) ? c : mine; }
;     if (sum == G) break;
;     __builtin_amdgcn_s_sleep(1);
;     if ((++sp & 255u) == 0u) { if (xb_ld(&bar[XB_TMO])) break; if (sp > XB_SPIN_CAP) { atomicAdd(&bar[XB_TMO], 1u); break; } }
;   }
.LBB0_1069:
	global_load_dword v15, v16, s[10:11] sc1
	s_waitcnt lgkmcnt(0)
	global_load_dword v0, v16, s[12:13] sc1
	global_load_dword v1, v16, s[16:17] sc1
	global_load_dword v2, v16, s[18:19] sc1
	global_load_dword v3, v16, s[20:21] sc1
	global_load_dword v4, v16, s[22:23] sc1
	global_load_dword v5, v16, s[24:25] sc1
	global_load_dword v6, v16, s[26:27] sc1
	global_load_dword v7, v16, s[30:31] sc1
	global_load_dword v8, v16, s[34:35] sc1
	global_load_dword v9, v16, s[36:37] sc1
	global_load_dword v10, v16, s[38:39] sc1
	global_load_dword v11, v16, s[40:41] sc1
	global_load_dword v12, v16, s[42:43] sc1
	global_load_dword v13, v16, s[44:45] sc1
	global_load_dword v14, v16, s[46:47] sc1
	s_mov_b64 s[48:49], -1
	s_mov_b64 s[50:51], -1
	s_waitcnt vmcnt(14)
	v_add_u32_e32 v17, v0, v15
	s_waitcnt vmcnt(13)
	v_add_u32_e32 v17, v17, v1
	s_waitcnt vmcnt(12)
	v_add_u32_e32 v17, v17, v2
	s_waitcnt vmcnt(11)
	v_add_u32_e32 v17, v17, v3
	s_waitcnt vmcnt(10)
	v_add_u32_e32 v17, v17, v4
	s_waitcnt vmcnt(9)
	v_add_u32_e32 v17, v17, v5
	s_waitcnt vmcnt(8)
	v_add_u32_e32 v17, v17, v6
	s_waitcnt vmcnt(7)
	v_add_u32_e32 v17, v17, v7
	s_waitcnt vmcnt(6)
	v_add_u32_e32 v17, v17, v8
	s_waitcnt vmcnt(5)
	v_add_u32_e32 v17, v17, v9
	s_waitcnt vmcnt(4)
	v_add_u32_e32 v17, v17, v10
	s_waitcnt vmcnt(3)
	v_add_u32_e32 v17, v17, v11
	s_waitcnt vmcnt(2)
	v_add_u32_e32 v17, v17, v12
	s_waitcnt vmcnt(1)
	v_add_u32_e32 v17, v17, v13
	s_waitcnt vmcnt(0)
	v_add_u32_e32 v17, v17, v14
	v_cmp_eq_u32_e32 vcc, s0, v17
	s_cbranch_vccnz .LBB0_1068
	s_and_b32 s2, s1, 0xff
	s_cmp_eq_u32 s2, 0
	s_mov_b64 s[52:53], -1
	s_sleep 6
	s_cbranch_scc0 .LBB0_1073
	global_load_dword v17, v16, s[8:9] sc1
	s_waitcnt vmcnt(0)
	v_cmp_eq_u32_e32 vcc, 0, v17
	s_cbranch_vccnz .LBB0_1075
	s_mov_b64 s[52:53], 0

; __device__ __forceinline__ unsigned xb_ld(unsigned* p)              { return __hip_atomic_load(p, __ATOMIC_RELAXED, __HIP_MEMORY_SCOPE_AGENT); }
; __device__ __forceinline__ unsigned xb_add(unsigned* p, unsigned v) { return __hip_atomic_fetch_add(p, v, __ATOMIC_RELAXED, __HIP_MEMORY_SCOPE_AGENT); }
; #define XB_SPIN(cond, bar) do { unsigned _sp = 0; while (cond) { __builtin_amdgcn_s_sleep(1); \
;     if ((++_sp & 255u) == 0u) { if (xb_ld(&(bar)[XB_TMO])) break; if (_sp > XB_SPIN_CAP) { atomicAdd(&(bar)[XB_TMO], 1u); break; } } } } while (0)
; __device__ __forceinline__ void xcd_barrier(const XcdBarrier& b) {
;     ...
;       else XB_SPIN(xb_ld(&bar[XB_TOPGEN]) == tg, bar);
;       __builtin_amdgcn_fence(__ATOMIC_ACQUIRE, "agent");
;       xb_add(&bar[XB_XGEN(b.x)], 1u);
;       asm volatile("s_waitcnt vmcnt(0)" ::: "memory");
;     } else {
;       XB_SPIN(xb_ld(&bar[XB_XGEN(b.x)]) == gen, bar);
.LBB0_1087:
	s_and_b32 s1, s0, 0xff
	s_mov_b64 s[24:25], -1
	s_cmp_lg_u32 s1, 0
	s_mov_b64 s[30:31], -1
	s_sleep 6
	s_cbranch_scc1 .LBB0_1090
	global_load_dword v2, v0, s[16:17] sc1
	s_waitcnt vmcnt(0)
	v_cmp_eq_u32_e32 vcc, 0, v2
	s_cbranch_vccnz .LBB0_1092
	s_mov_b64 s[30:31], 0
	s_mov_b64 s[26:27], -1

; __device__ __forceinline__ unsigned xb_ld(unsigned* p)              { return __hip_atomic_load(p, __ATOMIC_RELAXED, __HIP_MEMORY_SCOPE_AGENT); }
; __device__ __forceinline__ unsigned xb_add(unsigned* p, unsigned v) { return __hip_atomic_fetch_add(p, v, __ATOMIC_RELAXED, __HIP_MEMORY_SCOPE_AGENT); }
; #define XB_SPIN(cond, bar) do { unsigned _sp = 0; while (cond) { __builtin_amdgcn_s_sleep(1); \
;     if ((++_sp & 255u) == 0u) { if (xb_ld(&(bar)[XB_TMO])) break; if (_sp > XB_SPIN_CAP) { atomicAdd(&(bar)[XB_TMO], 1u); break; } } } } while (0)
; __device__ __forceinline__ void xcd_barrier(const XcdBarrier& b) {
;     ...
;       else XB_SPIN(xb_ld(&bar[XB_TOPGEN]) == tg, bar);
;       __builtin_amdgcn_fence(__ATOMIC_ACQUIRE, "agent");
;       xb_add(&bar[XB_XGEN(b.x)], 1u);
;       asm volatile("s_waitcnt vmcnt(0)" ::: "memory");
;     } else {
;       XB_SPIN(xb_ld(&bar[XB_XGEN(b.x)]) == gen, bar);
.LBB0_1104:
	s_and_b32 s1, s0, 0xff
	s_cmp_lg_u32 s1, 0
	s_mov_b64 s[26:27], -1
	s_sleep 6
	s_cbranch_scc1 .LBB0_1107
	global_load_dword v1, v0, s[16:17] sc1
	s_waitcnt vmcnt(0)
	v_cmp_eq_u32_e32 vcc, 0, v1
	s_cbranch_vccnz .LBB0_1109
	s_mov_b64 s[26:27], 0
	s_mov_b64 s[24:25], -1

; __device__ __forceinline__ unsigned xb_ld(unsigned* p)              { return __hip_atomic_load(p, __ATOMIC_RELAXED, __HIP_MEMORY_SCOPE_AGENT); }
; __device__ __forceinline__ void xcd_barrier_complete(unsigned* bar, unsigned x, unsigned& nloc, unsigned& nx) {
;     ...
;   for (;;) {
;     sum = 0u; cnt = 0u; mine = 0u;
; #pragma unroll
;     for (unsigned j = 0; j < 16; ++j) { const unsigned c = xb_ld(&bar[XB_XCNT(j)]); sum += c; cnt += (c > 0u) ? 1u : 0u; mine = (j == x) ? c : mine; }
;     if (sum == G) break;
;     __builtin_amdgcn_s_sleep(1);
;     if ((++sp & 255u) == 0u) { if (xb_ld(&bar[XB_TMO])) break; if (sp > XB_SPIN_CAP) { atomicAdd(&bar[XB_TMO], 1u); break; } }
;   }
.LBB0_1341:
	global_load_dword v15, v16, s[10:11] sc1
	s_waitcnt lgkmcnt(0)
	global_load_dword v0, v16, s[12:13] sc1
	global_load_dword v1, v16, s[14:15] sc1
	global_load_dword v2, v16, s[16:17] sc1
	global_load_dword v3, v16, s[18:19] sc1
	global_load_dword v4, v16, s[20:21] sc1
	global_load_dword v5, v16, s[22:23] sc1
	global_load_dword v6, v16, s[24:25] sc1
	global_load_dword v7, v16, s[26:27] sc1
	global_load_dword v8, v16, s[30:31] sc1
	global_load_dword v9, v16, s[34:35] sc1
	global_load_dword v10, v16, s[36:37] sc1
	global_load_dword v11, v16, s[38:39] sc1
	global_load_dword v12, v16, s[40:41] sc1
	global_load_dword v13, v16, s[42:43] sc1
	global_load_dword v14, v16, s[44:45] sc1
	s_mov_b64 s[46:47], -1
	s_mov_b64 s[48:49], -1
	s_waitcnt vmcnt(14)
	v_add_u32_e32 v17, v0, v15
	s_waitcnt vmcnt(13)
	v_add_u32_e32 v17, v17, v1
	s_waitcnt vmcnt(12)
	v_add_u32_e32 v17, v17, v2
	s_waitcnt vmcnt(11)
	v_add_u32_e32 v17, v17, v3
	s_waitcnt vmcnt(10)
	v_add_u32_e32 v17, v17, v4
	s_waitcnt vmcnt(9)
	v_add_u32_e32 v17, v17, v5
	s_waitcnt vmcnt(8)
	v_add_u32_e32 v17, v17, v6
	s_waitcnt vmcnt(7)
	v_add_u32_e32 v17, v17, v7
	s_waitcnt vmcnt(6)
	v_add_u32_e32 v17, v17, v8
	s_waitcnt vmcnt(5)
	v_add_u32_e32 v17, v17, v9
	s_waitcnt vmcnt(4)
	v_add_u32_e32 v17, v17, v10
	s_waitcnt vmcnt(3)
	v_add_u32_e32 v17, v17, v11
	s_waitcnt vmcnt(2)
	v_add_u32_e32 v17, v17, v12
	s_waitcnt vmcnt(1)
	v_add_u32_e32 v17, v17, v13
	s_waitcnt vmcnt(0)
	v_add_u32_e32 v17, v17, v14
	v_cmp_eq_u32_e32 vcc, s0, v17
	s_cbranch_vccnz .LBB0_1340
	s_and_b32 s2, s1, 0xff
	s_cmp_eq_u32 s2, 0
	s_mov_b64 s[50:51], -1
	s_sleep 6
	s_cbranch_scc0 .LBB0_1345
	global_load_dword v17, v16, s[8:9] sc1
	s_waitcnt vmcnt(0)
	v_cmp_eq_u32_e32 vcc, 0, v17
	s_cbranch_vccnz .LBB0_1347
	s_mov_b64 s[50:51], 0

; __device__ __forceinline__ unsigned xb_ld(unsigned* p)              { return __hip_atomic_load(p, __ATOMIC_RELAXED, __HIP_MEMORY_SCOPE_AGENT); }
; __device__ __forceinline__ unsigned xb_add(unsigned* p, unsigned v) { return __hip_atomic_fetch_add(p, v, __ATOMIC_RELAXED, __HIP_MEMORY_SCOPE_AGENT); }
; #define XB_SPIN(cond, bar) do { unsigned _sp = 0; while (cond) { __builtin_amdgcn_s_sleep(1); \
;     if ((++_sp & 255u) == 0u) { if (xb_ld(&(bar)[XB_TMO])) break; if (_sp > XB_SPIN_CAP) { atomicAdd(&(bar)[XB_TMO], 1u); break; } } } } while (0)
; __device__ __forceinline__ void xcd_barrier(const XcdBarrier& b) {
;     ...
;       else XB_SPIN(xb_ld(&bar[XB_TOPGEN]) == tg, bar);
;       __builtin_amdgcn_fence(__ATOMIC_ACQUIRE, "agent");
;       xb_add(&bar[XB_XGEN(b.x)], 1u);
;       asm volatile("s_waitcnt vmcnt(0)" ::: "memory");
;     } else {
;       XB_SPIN(xb_ld(&bar[XB_XGEN(b.x)]) == gen, bar);
.LBB0_1359:
	s_and_b32 s1, s0, 0xff
	s_mov_b64 s[22:23], -1
	s_cmp_lg_u32 s1, 0
	s_mov_b64 s[26:27], -1
	s_sleep 6
	s_cbranch_scc1 .LBB0_1362
	global_load_dword v2, v0, s[14:15] sc1
	s_waitcnt vmcnt(0)
	v_cmp_eq_u32_e32 vcc, 0, v2
	s_cbranch_vccnz .LBB0_1364
	s_mov_b64 s[26:27], 0
	s_mov_b64 s[24:25], -1

; __device__ __forceinline__ unsigned xb_ld(unsigned* p)              { return __hip_atomic_load(p, __ATOMIC_RELAXED, __HIP_MEMORY_SCOPE_AGENT); }
; __device__ __forceinline__ unsigned xb_add(unsigned* p, unsigned v) { return __hip_atomic_fetch_add(p, v, __ATOMIC_RELAXED, __HIP_MEMORY_SCOPE_AGENT); }
; #define XB_SPIN(cond, bar) do { unsigned _sp = 0; while (cond) { __builtin_amdgcn_s_sleep(1); \
;     if ((++_sp & 255u) == 0u) { if (xb_ld(&(bar)[XB_TMO])) break; if (_sp > XB_SPIN_CAP) { atomicAdd(&(bar)[XB_TMO], 1u); break; } } } } while (0)
; __device__ __forceinline__ void xcd_barrier(const XcdBarrier& b) {
;     ...
;       else XB_SPIN(xb_ld(&bar[XB_TOPGEN]) == tg, bar);
;       __builtin_amdgcn_fence(__ATOMIC_ACQUIRE, "agent");
;       xb_add(&bar[XB_XGEN(b.x)], 1u);
;       asm volatile("s_waitcnt vmcnt(0)" ::: "memory");
;     } else {
;       XB_SPIN(xb_ld(&bar[XB_XGEN(b.x)]) == gen, bar);
.LBB0_1376:
	s_and_b32 s1, s0, 0xff
	s_cmp_lg_u32 s1, 0
	s_mov_b64 s[24:25], -1
	s_sleep 6
	s_cbranch_scc1 .LBB0_1379
	global_load_dword v1, v0, s[14:15] sc1
	s_waitcnt vmcnt(0)
	v_cmp_eq_u32_e32 vcc, 0, v1
	s_cbranch_vccnz .LBB0_1381
	s_mov_b64 s[24:25], 0
	s_mov_b64 s[22:23], -1

; __device__ __forceinline__ unsigned xb_ld(unsigned* p)              { return __hip_atomic_load(p, __ATOMIC_RELAXED, __HIP_MEMORY_SCOPE_AGENT); }
; __device__ __forceinline__ void xcd_barrier_complete(unsigned* bar, unsigned x, unsigned& nloc, unsigned& nx) {
;     ...
;   for (;;) {
;     sum = 0u; cnt = 0u; mine = 0u;
; #pragma unroll
;     for (unsigned j = 0; j < 16; ++j) { const unsigned c = xb_ld(&bar[XB_XCNT(j)]); sum += c; cnt += (c > 0u) ? 1u : 0u; mine = (j == x) ? c : mine; }
;     if (sum == G) break;
;     __builtin_amdgcn_s_sleep(1);
;     if ((++sp & 255u) == 0u) { if (xb_ld(&bar[XB_TMO])) break; if (sp > XB_SPIN_CAP) { atomicAdd(&bar[XB_TMO], 1u); break; } }
;   }
.LBB0_1692:
	global_load_dword v15, v16, s[6:7] sc1
	s_waitcnt lgkmcnt(0)
	global_load_dword v0, v16, s[8:9] sc1
	global_load_dword v1, v16, s[10:11] sc1
	global_load_dword v2, v16, s[12:13] sc1
	global_load_dword v3, v16, s[14:15] sc1
	global_load_dword v4, v16, s[16:17] sc1
	global_load_dword v5, v16, s[18:19] sc1
	global_load_dword v6, v16, s[20:21] sc1
	global_load_dword v7, v16, s[22:23] sc1
	global_load_dword v8, v16, s[24:25] sc1
	global_load_dword v9, v16, s[26:27] sc1
	global_load_dword v10, v16, s[30:31] sc1
	global_load_dword v11, v16, s[34:35] sc1
	global_load_dword v12, v16, s[36:37] sc1
	global_load_dword v13, v16, s[38:39] sc1
	global_load_dword v14, v16, s[40:41] sc1
	s_mov_b64 s[42:43], -1
	s_mov_b64 s[44:45], -1
	s_waitcnt vmcnt(14)
	v_add_u32_e32 v17, v0, v15
	s_waitcnt vmcnt(13)
	v_add_u32_e32 v17, v17, v1
	s_waitcnt vmcnt(12)
	v_add_u32_e32 v17, v17, v2
	s_waitcnt vmcnt(11)
	v_add_u32_e32 v17, v17, v3
	s_waitcnt vmcnt(10)
	v_add_u32_e32 v17, v17, v4
	s_waitcnt vmcnt(9)
	v_add_u32_e32 v17, v17, v5
	s_waitcnt vmcnt(8)
	v_add_u32_e32 v17, v17, v6
	s_waitcnt vmcnt(7)
	v_add_u32_e32 v17, v17, v7
	s_waitcnt vmcnt(6)
	v_add_u32_e32 v17, v17, v8
	s_waitcnt vmcnt(5)
	v_add_u32_e32 v17, v17, v9
	s_waitcnt vmcnt(4)
	v_add_u32_e32 v17, v17, v10
	s_waitcnt vmcnt(3)
	v_add_u32_e32 v17, v17, v11
	s_waitcnt vmcnt(2)
	v_add_u32_e32 v17, v17, v12
	s_waitcnt vmcnt(1)
	v_add_u32_e32 v17, v17, v13
	s_waitcnt vmcnt(0)
	v_add_u32_e32 v17, v17, v14
	v_cmp_eq_u32_e32 vcc, s0, v17
	s_cbranch_vccnz .LBB0_1691
	s_and_b32 s33, s1, 0xff
	s_cmp_eq_u32 s33, 0
	s_mov_b64 s[46:47], -1
	s_sleep 6
	s_cbranch_scc0 .LBB0_1696
	global_load_dword v17, v16, s[4:5] sc1
	s_waitcnt vmcnt(0)
	v_cmp_eq_u32_e32 vcc, 0, v17
	s_cbranch_vccnz .LBB0_1698
	s_mov_b64 s[46:47], 0

; __device__ __forceinline__ unsigned xb_ld(unsigned* p)              { return __hip_atomic_load(p, __ATOMIC_RELAXED, __HIP_MEMORY_SCOPE_AGENT); }
; __device__ __forceinline__ unsigned xb_add(unsigned* p, unsigned v) { return __hip_atomic_fetch_add(p, v, __ATOMIC_RELAXED, __HIP_MEMORY_SCOPE_AGENT); }
; #define XB_SPIN(cond, bar) do { unsigned _sp = 0; while (cond) { __builtin_amdgcn_s_sleep(1); \
;     if ((++_sp & 255u) == 0u) { if (xb_ld(&(bar)[XB_TMO])) break; if (_sp > XB_SPIN_CAP) { atomicAdd(&(bar)[XB_TMO], 1u); break; } } } } while (0)
; __device__ __forceinline__ void xcd_barrier(const XcdBarrier& b) {
;     ...
;       else XB_SPIN(xb_ld(&bar[XB_TOPGEN]) == tg, bar);
;       __builtin_amdgcn_fence(__ATOMIC_ACQUIRE, "agent");
;       xb_add(&bar[XB_XGEN(b.x)], 1u);
;       asm volatile("s_waitcnt vmcnt(0)" ::: "memory");
;     } else {
;       XB_SPIN(xb_ld(&bar[XB_XGEN(b.x)]) == gen, bar);
.LBB0_1710:
	s_and_b32 s1, s0, 0xff
	s_mov_b64 s[18:19], -1
	s_cmp_lg_u32 s1, 0
	s_mov_b64 s[22:23], -1
	s_sleep 6
	s_cbranch_scc1 .LBB0_1713
	global_load_dword v2, v0, s[10:11] sc1
	s_waitcnt vmcnt(0)
	v_cmp_eq_u32_e32 vcc, 0, v2
	s_cbranch_vccnz .LBB0_1715
	s_mov_b64 s[22:23], 0
	s_mov_b64 s[20:21], -1

; __device__ __forceinline__ unsigned xb_ld(unsigned* p)              { return __hip_atomic_load(p, __ATOMIC_RELAXED, __HIP_MEMORY_SCOPE_AGENT); }
; __device__ __forceinline__ unsigned xb_add(unsigned* p, unsigned v) { return __hip_atomic_fetch_add(p, v, __ATOMIC_RELAXED, __HIP_MEMORY_SCOPE_AGENT); }
; #define XB_SPIN(cond, bar) do { unsigned _sp = 0; while (cond) { __builtin_amdgcn_s_sleep(1); \
;     if ((++_sp & 255u) == 0u) { if (xb_ld(&(bar)[XB_TMO])) break; if (_sp > XB_SPIN_CAP) { atomicAdd(&(bar)[XB_TMO], 1u); break; } } } } while (0)
; __device__ __forceinline__ void xcd_barrier(const XcdBarrier& b) {
;     ...
;       else XB_SPIN(xb_ld(&bar[XB_TOPGEN]) == tg, bar);
;       __builtin_amdgcn_fence(__ATOMIC_ACQUIRE, "agent");
;       xb_add(&bar[XB_XGEN(b.x)], 1u);
;       asm volatile("s_waitcnt vmcnt(0)" ::: "memory");
;     } else {
;       XB_SPIN(xb_ld(&bar[XB_XGEN(b.x)]) == gen, bar);
.LBB0_1727:
	s_and_b32 s1, s0, 0xff
	s_cmp_lg_u32 s1, 0
	s_mov_b64 s[20:21], -1
	s_sleep 6
	s_cbranch_scc1 .LBB0_1730
	global_load_dword v1, v0, s[10:11] sc1
	s_waitcnt vmcnt(0)
	v_cmp_eq_u32_e32 vcc, 0, v1
	s_cbranch_vccnz .LBB0_1732
	s_mov_b64 s[20:21], 0
	s_mov_b64 s[18:19], -1
